# same as the pool-in-LDS version, but the never-executed non-FIXED window prologue is restored to the baseline instruction order (robustness; no timing change expected)
# speedup vs baseline: 1.0013x; 1.0013x over previous
.LBB0_427:
	v_readlane_b32 s2, v254, 7
	s_lshl_b32 s1, s1, 8
	s_add_i32 s6, s0, s2
	s_and_b32 s7, s1, 0x700
	s_lshl_b32 s0, s0, 11
	v_readlane_b32 s1, v253, 40
	s_add_i32 s0, s0, s1
	s_or_b32 s4, s7, s0
	s_add_i32 s0, s8, s25
	v_readlane_b32 s76, v253, 4
	s_ashr_i32 s1, s0, 31
	v_readlane_b32 s80, v253, 8
	v_readlane_b32 s81, v253, 9
	s_ashr_i32 s2, s8, 2
	s_min_u32 s18, s7, 0x680
	s_lshl_b64 s[0:1], s[0:1], 2
	s_mov_b64 s[12:13], s[80:81]
	v_mov_b32_e32 v0, 0x80
	s_add_u32 s0, s12, s0
	v_sub_u32_e64 v0, s7, v0 clamp
	s_addc_u32 s1, s13, s1
	v_readfirstlane_b32 s28, v0
	global_load_dword v48, v1, s[0:1]
	s_mul_i32 s0, s6, 20
	s_ashr_i32 s1, s0, 31
	s_lshl_b64 s[0:1], s[0:1], 2
	s_add_u32 s5, s54, s0
	s_addc_u32 s10, s58, s1
	s_ashr_i32 s9, s8, 31
	s_lshl_b64 s[0:1], s[8:9], 2
	s_add_u32 s0, s5, s0
	s_addc_u32 s1, s10, s1
	s_ashr_i32 s3, s2, 31
	v_readlane_b32 s77, v253, 5
	v_readlane_b32 s80, v255, 3
	v_readlane_b32 s76, v255, 5
	v_readlane_b32 s81, v255, 4
	v_readlane_b32 s77, v255, 6
	v_readlane_b32 s78, v253, 6
	v_readlane_b32 s79, v253, 7
	v_readlane_b32 s82, v253, 10
	v_readlane_b32 s83, v253, 11
	global_load_dword v49, v1, s[0:1] sc1
	s_lshl_b64 s[0:1], s[2:3], 2
	s_add_u32 s0, s5, s0
	s_addc_u32 s1, s10, s1
	s_ashr_i32 s5, s4, 31
	s_lshl_b64 s[4:5], s[4:5], 11
	global_load_dword v50, v1, s[0:1] offset:64 sc1
	s_add_u32 s3, s36, s4
	s_addc_u32 s10, s37, s5
	s_lshl_b32 s8, s8, 6
	s_ashr_i32 s9, s8, 31
	s_lshl_b64 s[8:9], s[8:9], 1
	s_add_u32 s14, s3, s8
	s_addc_u32 s15, s10, s9
	s_mul_i32 s10, s6, 0x120000
	s_mul_hi_i32 s3, s6, 0x120000
	s_add_u32 s12, s38, s10
	s_addc_u32 s3, s39, s3
	s_lshl_b32 s10, s2, 6
	s_ashr_i32 s11, s10, 31
	s_lshl_b64 s[10:11], s[10:11], 1
	s_add_u32 s12, s12, s10
	s_addc_u32 s13, s3, s11
	s_lshl_b32 s3, s6, 2
	s_add_i32 s2, s3, s2
	s_mul_hi_i32 s3, s2, 0x48000
	s_mul_i32 s2, s2, 0x48000
	s_add_u32 s16, s57, s2
	s_addc_u32 s17, s88, s3
	s_add_u32 s2, s84, s4
	s_addc_u32 s3, s85, s5
	s_add_u32 s10, s2, s8
	s_addc_u32 s11, s3, s9
	s_sub_i32 s29, s18, s28
	s_addk_i32 s29, 0x180
	s_lshr_b32 s6, s28, 6
	s_ashr_i32 s27, s29, 6
	v_mov_b32_e32 v17, v209
	v_mov_b32_e32 v23, v1
	v_readfirstlane_b32 s0, v17
	s_ashr_i32 s0, s0, 1
	s_and_b32 s4, s0, 0xffffffe0
	s_add_i32 s20, s4, s7
	v_mov_b32_e32 v0, s0
	s_movk_i32 s0, 0xffe0
	s_cmp_gt_i32 s27, 0
	v_bfi_b32 v2, s0, v0, v17
	s_cselect_b64 s[0:1], -1, 0
	s_sub_i32 s5, 0x800, s29
	v_ashrrev_i32_e32 v3, 31, v2
	s_cmp_lt_i32 s27, 1
	v_bfe_u32 v226, v17, 5, 1
	v_lshlrev_b64 v[188:189], 11, v[2:3]
	s_cselect_b64 s[2:3], -1, 0
	v_lshl_add_u64 v[2:3], s[14:15], 0, v[188:189]
	v_lshlrev_b32_e32 v0, 4, v226
	s_and_b64 s[8:9], s[2:3], exec
	v_lshl_add_u64 v[14:15], v[2:3], 0, v[0:1]
	v_ashrrev_i32_e32 v194, 3, v17
	s_cselect_b32 s68, s5, s28
	global_load_dwordx4 v[2:5], v[14:15], off
	global_load_dwordx4 v[6:9], v[14:15], off offset:32
	global_load_dwordx4 v[10:13], v[14:15], off offset:64
	global_load_dwordx4 v[176:179], v[14:15], off offset:96
	v_add_u32_e32 v14, s68, v194
	v_ashrrev_i32_e32 v15, 31, v14
	v_and_b32_e32 v16, 7, v17
	v_lshlrev_b64 v[14:15], 9, v[14:15]
	s_or_b32 s5, s6, 1
	s_sub_i32 s8, 33, s27
	v_lshl_add_u64 v[14:15], s[12:13], 0, v[14:15]
	v_lshlrev_b32_e32 v22, 4, v16
	s_cmp_gt_i32 s27, 1
	v_lshl_add_u64 v[14:15], v[14:15], 0, v[22:23]
	s_cselect_b32 s5, s5, s8
	global_load_dwordx4 v[18:21], v[14:15], off
	v_lshl_add_u32 v14, s5, 6, v194
	v_ashrrev_i32_e32 v15, 31, v14
	v_lshlrev_b64 v[14:15], 9, v[14:15]
	v_lshl_add_u64 v[14:15], s[12:13], 0, v[14:15]
	v_lshl_add_u64 v[24:25], v[14:15], 0, v[22:23]
	v_mov_b64_e32 v[14:15], s[16:17]
	s_movk_i32 s5, 0x1200
	v_mad_i64_i32 v[14:15], s[8:9], v194, s5, v[14:15]
	v_lshl_add_u64 v[26:27], s[68:69], 1, v[14:15]
	v_lshl_add_u64 v[26:27], v[26:27], 0, v[22:23]
	global_load_dwordx4 v[180:183], v[26:27], off
	global_load_dwordx4 v[184:187], v[24:25], off
	s_waitcnt vmcnt(7)
	v_mul_f32_e32 v227, 0x3fb8aa3b, v48
	v_mul_f32_e32 v51, v49, v50
	s_mov_b32 s32, 0xf800000
	v_cmp_gt_f32_e32 vcc, s32, v51
	v_mul_f32_e32 v52, 0x4f800000, v51
	s_nop 0
	v_cndmask_b32_e32 v51, v51, v52, vcc
	v_sqrt_f32_e32 v52, v51
	s_nop 0
	v_add_u32_e32 v53, -1, v52
	v_fma_f32 v54, -v53, v52, v51
	v_cmp_ge_f32_e64 s[98:99], 0, v54
	v_add_u32_e32 v54, 1, v52
	s_nop 0
	v_cndmask_b32_e64 v53, v52, v53, s[98:99]
	v_fma_f32 v52, -v54, v52, v51
	v_cmp_lt_f32_e64 s[98:99], 0, v52
	s_nop 1
	v_cndmask_b32_e64 v52, v53, v54, s[98:99]
	v_mul_f32_e32 v53, 0x37800000, v52
	v_cndmask_b32_e32 v52, v52, v53, vcc
	v_mov_b32_e32 v53, 0x260
	v_cmp_class_f32_e32 vcc, v51, v53
	s_mov_b32 s32, 0x42480000
	s_nop 0
	v_cndmask_b32_e32 v51, v52, v51, vcc
	v_fmamk_f32 v51, v51, 0x3f828f5c, v214
	v_max_f32_e32 v51, v51, v227
	v_cmp_ge_f32_e32 vcc, s32, v51
	s_mov_b32 s32, 0xc2700000
	v_cmp_le_f32_e64 s[98:99], s32, v227
	s_and_b64 s[98:99], vcc, s[98:99]
	s_andn2_b64 vcc, exec, s[98:99]
	s_cbranch_vccz .Lwin_fx
	s_waitcnt vmcnt(0)
	s_mov_b64 s[2:3], -1
	v_mov_b32_e32 v18, v209
	v_mov_b32_e32 v21, v1
	v_readfirstlane_b32 s0, v18
	s_ashr_i32 s0, s0, 1
	s_and_b32 s4, s0, 0xffffffe0
	s_add_i32 s35, s4, s7
	v_mov_b32_e32 v0, s0
	s_movk_i32 s0, 0xffe0
	s_cmp_gt_i32 s27, 0
	v_bfi_b32 v2, s0, v0, v18
	s_cselect_b64 s[0:1], -1, 0
	s_sub_i32 s5, 0x800, s29
	v_ashrrev_i32_e32 v3, 31, v2
	s_cmp_lt_i32 s27, 1
	v_bfe_u32 v226, v18, 5, 1
	v_lshlrev_b64 v[14:15], 11, v[2:3]
	s_cselect_b64 s[2:3], -1, 0
	v_lshl_add_u64 v[2:3], s[14:15], 0, v[14:15]
	v_lshlrev_b32_e32 v0, 4, v226
	s_and_b64 s[8:9], s[2:3], exec
	v_lshl_add_u64 v[16:17], v[2:3], 0, v[0:1]
	v_ashrrev_i32_e32 v228, 3, v18
	s_cselect_b32 s68, s5, s28
	global_load_dwordx4 v[2:5], v[16:17], off
	global_load_dwordx4 v[6:9], v[16:17], off offset:32
	global_load_dwordx4 v[10:13], v[16:17], off offset:64
	global_load_dwordx4 v[192:195], v[16:17], off offset:96
	v_add_u32_e32 v16, s68, v228
	v_ashrrev_i32_e32 v17, 31, v16
	v_and_b32_e32 v35, 7, v18
	v_lshlrev_b64 v[16:17], 9, v[16:17]
	v_lshl_add_u64 v[16:17], s[12:13], 0, v[16:17]
	v_lshlrev_b32_e32 v20, 4, v35
	v_lshl_add_u64 v[16:17], v[16:17], 0, v[20:21]
	v_and_b32_e32 v34, 31, v18
	global_load_dwordx4 v[16:19], v[16:17], off
	s_movk_i32 s5, 0x90
	v_mul_lo_u32 v22, v228, s5
	s_or_b32 s5, s6, 1
	s_sub_i32 s8, 33, s27
	s_cmp_gt_i32 s27, 1
	v_add3_u32 v229, 0, v22, v20
	s_cselect_b32 s5, s5, s8
	s_add_i32 s30, s35, 0xffffff80
	v_cmp_eq_u32_e32 vcc, 0, v226
	v_xor_b32_e32 v80, 0x80000000, v227
	v_mov_b32_e32 v232, 1.0
	v_cndmask_b32_e64 v231, 0, 1.0, vcc
	v_mul_u32_u24_e32 v230, 0x90, v34
	s_waitcnt vmcnt(0)
	ds_write_b128 v229, v[16:19]
	v_lshl_add_u32 v16, s5, 6, v228
	v_ashrrev_i32_e32 v17, 31, v16
	v_lshlrev_b64 v[16:17], 9, v[16:17]
	v_lshl_add_u64 v[16:17], s[12:13], 0, v[16:17]
	v_lshl_add_u64 v[16:17], v[16:17], 0, v[20:21]
	global_load_dwordx4 v[196:199], v[16:17], off
	v_mov_b64_e32 v[16:17], s[16:17]
	s_movk_i32 s5, 0x1200
	v_mad_i64_i32 v[32:33], s[8:9], v228, s5, v[16:17]
	v_lshl_add_u64 v[16:17], s[68:69], 1, v[32:33]
	v_lshl_add_u64 v[16:17], v[16:17], 0, v[20:21]
	global_load_dwordx4 v[200:203], v[16:17], off
	s_or_b32 s5, s28, 63
	s_cmp_ge_i32 s5, s30
	s_cselect_b64 s[8:9], -1, 0
	s_add_i32 s31, s35, 0x9f
	s_cmp_le_i32 s28, s31
	s_cselect_b64 s[18:19], -1, 0
	s_and_b64 s[8:9], s[8:9], s[18:19]
	s_or_b64 s[8:9], s[2:3], s[8:9]
	s_andn2_b64 vcc, exec, s[8:9]
	s_waitcnt lgkmcnt(0)
	s_barrier
	s_cbranch_vccnz .LBB0_435
	v_add3_u32 v48, 0, v230, v0
	ds_read_b128 v[16:19], v48
	ds_read_b128 v[20:23], v48 offset:32
	ds_read_b128 v[24:27], v48 offset:4608
	ds_read_b128 v[28:31], v48 offset:4640
	ds_read_b128 v[36:39], v48 offset:64
	ds_read_b128 v[40:43], v48 offset:96
	ds_read_b128 v[44:47], v48 offset:4672
	ds_read_b128 v[96:99], v48 offset:4704
	v_mov_b32_e32 v81, v80
	v_mov_b32_e32 v82, v80
	v_mov_b32_e32 v83, v80
	v_mov_b32_e32 v84, v80
	v_mov_b32_e32 v85, v80
	v_mov_b32_e32 v86, v80
	v_mov_b32_e32 v87, v80
	v_mov_b32_e32 v88, v80
	v_mov_b32_e32 v89, v80
	v_mov_b32_e32 v90, v80
	v_mov_b32_e32 v91, v80
	v_mov_b32_e32 v92, v80
	v_mov_b32_e32 v93, v80
	v_mov_b32_e32 v94, v80
	v_mov_b32_e32 v95, v80
	v_mov_b64_e32 v[64:65], v[80:81]
	v_mov_b64_e32 v[66:67], v[82:83]
	v_mov_b64_e32 v[68:69], v[84:85]
	v_mov_b64_e32 v[70:71], v[86:87]
	v_mov_b64_e32 v[72:73], v[88:89]
	v_mov_b64_e32 v[74:75], v[90:91]
	v_mov_b64_e32 v[76:77], v[92:93]
	v_mov_b64_e32 v[78:79], v[94:95]
	s_waitcnt lgkmcnt(7)
	v_mfma_f32_32x32x16_bf16 v[48:63], v[16:19], v[2:5], v[80:95]
	s_andn2_b64 vcc, exec, s[0:1]
	s_waitcnt lgkmcnt(5)
	v_mfma_f32_32x32x16_bf16 v[64:79], v[24:27], v[2:5], v[64:79]
	v_mfma_f32_32x32x16_bf16 v[48:63], v[20:23], v[6:9], v[48:63]
	s_waitcnt lgkmcnt(4)
	v_mfma_f32_32x32x16_bf16 v[64:79], v[28:31], v[6:9], v[64:79]
	s_waitcnt lgkmcnt(3)
	v_mfma_f32_32x32x16_bf16 v[48:63], v[36:39], v[10:13], v[48:63]
	s_waitcnt lgkmcnt(1)
	v_mfma_f32_32x32x16_bf16 v[64:79], v[44:47], v[10:13], v[64:79]
	v_mfma_f32_32x32x16_bf16 v[48:63], v[40:43], v[192:195], v[48:63]
	s_waitcnt lgkmcnt(0)
	v_mfma_f32_32x32x16_bf16 v[64:79], v[96:99], v[192:195], v[64:79]
	s_cbranch_vccnz .LBB0_432
	s_add_i32 s0, s35, 0xffffff9f
	s_cmp_lt_i32 s28, s0
	s_cselect_b64 s[0:1], -1, 0
	s_add_i32 s2, s35, 0x41
	s_cmp_gt_i32 s28, s2
	s_cselect_b64 s[2:3], -1, 0
	s_or_b64 s[0:1], s[0:1], s[2:3]
	s_andn2_b64 vcc, exec, s[0:1]
	s_cbranch_vccnz .LBB0_432
	v_or_b32_e32 v16, s35, v34
	v_lshl_or_b32 v17, v226, 2, s28
	v_sub_u32_e32 v16, v16, v17
	v_add_u32_e32 v17, 0x80, v16
	s_movk_i32 s0, 0x101
	v_cmp_gt_u32_e32 vcc, s0, v17
	v_add_u32_e32 v17, 0xffffff5f, v16
	s_movk_i32 s0, 0xfefe
	v_cndmask_b32_e32 v48, v216, v48, vcc
	v_cmp_lt_u32_e32 vcc, s0, v17
	v_add_u32_e32 v17, 0xffffff7e, v16
	s_nop 0
	v_cndmask_b32_e32 v64, v216, v64, vcc
	v_cmp_lt_u32_e32 vcc, s0, v17
	v_add_u32_e32 v17, 0xffffff5e, v16
	s_nop 0
	v_cndmask_b32_e32 v49, v216, v49, vcc
	v_cmp_lt_u32_e32 vcc, s0, v17
	v_add_u32_e32 v17, 0xffffff7d, v16
	s_nop 0
	v_cndmask_b32_e32 v65, v216, v65, vcc
	v_cmp_lt_u32_e32 vcc, s0, v17
	v_add_u32_e32 v17, 0xffffff5d, v16
	s_nop 0
	v_cndmask_b32_e32 v50, v216, v50, vcc
	v_cmp_lt_u32_e32 vcc, s0, v17
	v_add_u32_e32 v17, 0xffffff7c, v16
	s_nop 0
	v_cndmask_b32_e32 v66, v216, v66, vcc
	v_cmp_lt_u32_e32 vcc, s0, v17
	v_add_u32_e32 v17, 0xffffff5c, v16
	s_nop 0
	v_cndmask_b32_e32 v51, v216, v51, vcc
	v_cmp_lt_u32_e32 vcc, s0, v17
	v_add_u32_e32 v17, 0xffffff77, v16
	s_nop 0
	v_cndmask_b32_e32 v67, v216, v67, vcc
	v_cmp_lt_u32_e32 vcc, s0, v17
	v_add_u32_e32 v17, 0xffffff57, v16
	s_nop 0
	v_cndmask_b32_e32 v52, v216, v52, vcc
	v_cmp_lt_u32_e32 vcc, s0, v17
	v_add_u32_e32 v17, 0xffffff76, v16
	s_nop 0
	v_cndmask_b32_e32 v68, v216, v68, vcc
	v_cmp_lt_u32_e32 vcc, s0, v17
	v_add_u32_e32 v17, 0xffffff56, v16
	s_nop 0
	v_cndmask_b32_e32 v53, v216, v53, vcc
	v_cmp_lt_u32_e32 vcc, s0, v17
	v_add_u32_e32 v17, 0xffffff75, v16
	s_nop 0
	v_cndmask_b32_e32 v69, v216, v69, vcc
	v_cmp_lt_u32_e32 vcc, s0, v17
	v_add_u32_e32 v17, 0xffffff55, v16
	s_nop 0
	v_cndmask_b32_e32 v54, v216, v54, vcc
	v_cmp_lt_u32_e32 vcc, s0, v17
	v_add_u32_e32 v17, 0xffffff74, v16
	s_nop 0
	v_cndmask_b32_e32 v70, v216, v70, vcc
	v_cmp_lt_u32_e32 vcc, s0, v17
	v_add_u32_e32 v17, 0xffffff54, v16
	s_nop 0
	v_cndmask_b32_e32 v55, v216, v55, vcc
	v_cmp_lt_u32_e32 vcc, s0, v17
	v_add_u32_e32 v17, 0xffffff6f, v16
	s_nop 0
	v_cndmask_b32_e32 v71, v216, v71, vcc
	v_cmp_lt_u32_e32 vcc, s0, v17
	v_add_u32_e32 v17, 0xffffff4f, v16
	s_nop 0
	v_cndmask_b32_e32 v56, v216, v56, vcc
	v_cmp_lt_u32_e32 vcc, s0, v17
	v_add_u32_e32 v17, 0xffffff6e, v16
	s_nop 0
	v_cndmask_b32_e32 v72, v216, v72, vcc
	v_cmp_lt_u32_e32 vcc, s0, v17
	v_add_u32_e32 v17, 0xffffff4e, v16
	s_nop 0
	v_cndmask_b32_e32 v57, v216, v57, vcc
	v_cmp_lt_u32_e32 vcc, s0, v17
	v_add_u32_e32 v17, 0xffffff6d, v16
	s_nop 0
	v_cndmask_b32_e32 v73, v216, v73, vcc
	v_cmp_lt_u32_e32 vcc, s0, v17
	v_add_u32_e32 v17, 0xffffff4d, v16
	s_nop 0
	v_cndmask_b32_e32 v58, v216, v58, vcc
	v_cmp_lt_u32_e32 vcc, s0, v17
	v_add_u32_e32 v17, 0xffffff6c, v16
	s_nop 0
	v_cndmask_b32_e32 v74, v216, v74, vcc
	v_cmp_lt_u32_e32 vcc, s0, v17
	v_add_u32_e32 v17, 0xffffff4c, v16
	s_nop 0
	v_cndmask_b32_e32 v59, v216, v59, vcc
	v_cmp_lt_u32_e32 vcc, s0, v17
	v_add_u32_e32 v17, 0xffffff67, v16
	s_nop 0
	v_cndmask_b32_e32 v75, v216, v75, vcc
	v_cmp_lt_u32_e32 vcc, s0, v17
	v_add_u32_e32 v17, 0xffffff47, v16
	s_nop 0
	v_cndmask_b32_e32 v60, v216, v60, vcc
	v_cmp_lt_u32_e32 vcc, s0, v17
	v_add_u32_e32 v17, 0xffffff66, v16
	s_nop 0
	v_cndmask_b32_e32 v76, v216, v76, vcc
	v_cmp_lt_u32_e32 vcc, s0, v17
	v_add_u32_e32 v17, 0xffffff46, v16
	s_nop 0
	v_cndmask_b32_e32 v61, v216, v61, vcc
	v_cmp_lt_u32_e32 vcc, s0, v17
	v_add_u32_e32 v17, 0xffffff65, v16
	s_nop 0
	v_cndmask_b32_e32 v77, v216, v77, vcc
	v_cmp_lt_u32_e32 vcc, s0, v17
	v_add_u32_e32 v17, 0xffffff45, v16
	s_nop 0
	v_cndmask_b32_e32 v62, v216, v62, vcc
	v_cmp_lt_u32_e32 vcc, s0, v17
	v_add_u32_e32 v17, 0xffffff64, v16
	v_add_u32_e32 v16, 0xffffff44, v16
	v_cndmask_b32_e32 v78, v216, v78, vcc
	v_cmp_lt_u32_e32 vcc, s0, v17
	s_nop 1
	v_cndmask_b32_e32 v63, v216, v63, vcc
	v_cmp_lt_u32_e32 vcc, s0, v16
	s_nop 1
	v_cndmask_b32_e32 v79, v216, v79, vcc
